# GLA gate-table loops (stage 1 and 3): pairs of time steps interleaved for 2-way ILP (second stream on renamed VGPRs/SGPR masks), cumulative sum order unchanged
# baseline (speedup 1.0000x reference)
.LBB0_495:
	s_waitcnt vmcnt(0)
	s_add_i32 s0, s36, 3
	s_add_i32 s100, s36, 2
	v_mov_b32_e32 v18, s0
	s_add_i32 s101, s19, 1
	v_mov_b32_e32 v19, s19
	v_mov_b32_e32 v40, s100
	v_cndmask_b32_e64 v36, v18, v19, s[10:11]
	v_mov_b32_e32 v41, s101
	v_lshl_add_u32 v30, v36, 7, v194
	v_cndmask_b32_e64 v58, v40, v41, s[10:11]
	ds_read_b128 v[18:21], v30
	v_lshl_add_u32 v52, v58, 7, v194
	ds_read_b128 v[22:25], v30 offset:16
	ds_read_b128 v[40:43], v52
	ds_read_b128 v[26:29], v30 offset:32
	ds_read_b128 v[44:47], v52 offset:16
	ds_read_b128 v[30:33], v30 offset:48
	ds_read_b128 v[48:51], v52 offset:32
	s_waitcnt lgkmcnt(0)
	ds_read_b128 v[52:55], v52 offset:48
	v_mov_b32_e32 v34, v18
	s_waitcnt lgkmcnt(0)
	s_waitcnt lgkmcnt(0)
	v_mov_b32_e32 v56, v40
	v_mov_b32_e32 v35, v22
	s_waitcnt lgkmcnt(0)
	v_mov_b32_e32 v22, v19
	v_mov_b32_e32 v57, v44
	v_pk_mul_f32 v[18:19], v[2:3], v[22:23]
	v_mov_b32_e32 v44, v41
	v_mov_b32_e32 v22, v20
	v_pk_mul_f32 v[40:41], v[2:3], v[44:45]
	v_pk_fma_f32 v[18:19], v[0:1], v[34:35], v[18:19]
	v_mov_b32_e32 v44, v42
	v_mov_b32_e32 v23, v24
	v_pk_fma_f32 v[40:41], v[0:1], v[56:57], v[40:41]
	v_pk_fma_f32 v[18:19], v[4:5], v[22:23], v[18:19]
	v_mov_b32_e32 v45, v46
	v_mov_b32_e32 v24, v21
	v_pk_fma_f32 v[40:41], v[4:5], v[44:45], v[40:41]
	v_pk_fma_f32 v[18:19], v[6:7], v[24:25], v[18:19]
	v_mov_b32_e32 v46, v43
	v_add_f32_e32 v18, v16, v18
	v_pk_fma_f32 v[40:41], v[6:7], v[46:47], v[40:41]
	v_add_f32_e32 v22, v18, v19
	s_nop 0
	s_waitcnt lgkmcnt(0)
	v_add_f32_e32 v40, v16, v40
	v_mov_b32_e32 v19, v30
	v_add_f32_e32 v44, v40, v41
	v_mov_b32_e32 v30, v27
	s_waitcnt lgkmcnt(0)
	v_mov_b32_e32 v18, v26
	v_mov_b32_e32 v41, v52
	v_pk_mul_f32 v[20:21], v[10:11], v[30:31]
	v_mov_b32_e32 v52, v49
	s_nop 0
	v_mov_b32_e32 v40, v48
	v_pk_fma_f32 v[18:19], v[8:9], v[18:19], v[20:21]
	v_pk_mul_f32 v[42:43], v[10:11], v[52:53]
	v_mov_b32_e32 v20, v28
	s_nop 0
	v_mov_b32_e32 v21, v32
	v_pk_fma_f32 v[40:41], v[8:9], v[40:41], v[42:43]
	v_pk_fma_f32 v[18:19], v[12:13], v[20:21], v[18:19]
	v_mov_b32_e32 v42, v50
	v_mov_b32_e32 v32, v29
	v_mov_b32_e32 v43, v54
	v_pk_fma_f32 v[18:19], v[14:15], v[32:33], v[18:19]
	v_pk_fma_f32 v[40:41], v[12:13], v[42:43], v[40:41]
	s_nop 0
	v_mov_b32_e32 v54, v51
	v_add_f32_e32 v18, v22, v18
	v_pk_fma_f32 v[40:41], v[14:15], v[54:55], v[40:41]
	v_add_f32_e32 v18, v18, v19
	s_nop 0
	v_min_f32_e32 v19, 0, v18
	v_add_f32_e32 v40, v44, v40
	v_mul_f32_e64 v18, |v18|, s29
	v_add_f32_e32 v40, v40, v41
	v_exp_f32_e32 v18, v18
	v_min_f32_e32 v41, 0, v40
	s_nop 0
	v_mul_f32_e64 v40, |v40|, s29
	v_add_f32_e32 v18, 1.0, v18
	v_exp_f32_e32 v40, v40
	v_cmp_gt_f32_e32 vcc, s30, v18
	s_nop 0
	s_nop 1
	v_add_f32_e32 v40, 1.0, v40
	v_cndmask_b32_e64 v20, 0, 32, vcc
	v_cmp_gt_f32_e64 s[98:99], s30, v40
	v_ldexp_f32 v18, v18, v20
	s_nop 1
	v_log_f32_e32 v18, v18
	v_cndmask_b32_e64 v42, 0, 32, s[98:99]
	s_nop 0
	v_ldexp_f32 v40, v40, v42
	v_mul_f32_e32 v20, 0x3f317217, v18
	v_log_f32_e32 v40, v40
	v_fma_f32 v20, v18, s31, -v20
	s_nop 0
	v_fmac_f32_e32 v20, 0x3377d1cf, v18
	v_mul_f32_e32 v42, 0x3f317217, v40
	v_fmac_f32_e32 v20, 0x3f317217, v18
	v_fma_f32 v42, v40, s31, -v42
	v_cmp_lt_f32_e64 s[0:1], |v18|, s34
	v_fmac_f32_e32 v42, 0x3377d1cf, v40
	s_nop 1
	v_fmac_f32_e32 v42, 0x3f317217, v40
	v_cndmask_b32_e64 v18, v18, v20, s[0:1]
	v_cmp_lt_f32_e64 s[100:101], |v40|, s34
	v_cndmask_b32_e32 v20, 0, v239, vcc
	s_nop 1
	v_sub_f32_e32 v18, v18, v20
	v_cndmask_b32_e64 v40, v40, v42, s[100:101]
	v_sub_f32_e32 v18, v19, v18
	v_cndmask_b32_e64 v42, 0, v239, s[98:99]
	v_sub_f32_e32 v40, v40, v42
	v_sub_f32_e32 v40, v41, v40
	v_fmac_f32_e32 v17, 0x3d800000, v18
	v_lshl_add_u32 v18, v36, 9, v193
	ds_write_b32 v18, v17
	v_lshl_add_u32 v59, v58, 9, v193
	s_nop 1
	v_fmac_f32_e32 v17, 0x3d800000, v40
	ds_write_b32 v59, v17
	s_add_i32 s0, s36, 1
	s_add_i32 s100, s19, 3
	s_add_i32 s1, s19, 2
	v_mov_b32_e32 v40, s36
	v_mov_b32_e32 v18, s0
	v_mov_b32_e32 v41, s100
	v_mov_b32_e32 v19, s1
	v_cndmask_b32_e64 v58, v40, v41, s[10:11]
	v_cndmask_b32_e64 v36, v18, v19, s[10:11]
	v_lshl_add_u32 v52, v58, 7, v194
	v_lshl_add_u32 v30, v36, 7, v194
	ds_read_b128 v[40:43], v52
	ds_read_b128 v[18:21], v30
	ds_read_b128 v[44:47], v52 offset:16
	ds_read_b128 v[22:25], v30 offset:16
	ds_read_b128 v[48:51], v52 offset:32
	ds_read_b128 v[26:29], v30 offset:32
	ds_read_b128 v[52:55], v52 offset:48
	ds_read_b128 v[30:33], v30 offset:48
	s_add_i32 s36, s36, -4
	s_waitcnt lgkmcnt(0)
	s_waitcnt lgkmcnt(0)
	v_mov_b32_e32 v34, v18
	v_mov_b32_e32 v56, v40
	s_waitcnt lgkmcnt(0)
	s_waitcnt lgkmcnt(0)
	v_mov_b32_e32 v35, v22
	v_mov_b32_e32 v57, v44
	v_mov_b32_e32 v22, v19
	v_mov_b32_e32 v44, v41
	v_pk_mul_f32 v[18:19], v[2:3], v[22:23]
	v_pk_mul_f32 v[40:41], v[2:3], v[44:45]
	v_mov_b32_e32 v22, v20
	v_mov_b32_e32 v44, v42
	v_pk_fma_f32 v[18:19], v[0:1], v[34:35], v[18:19]
	v_pk_fma_f32 v[40:41], v[0:1], v[56:57], v[40:41]
	v_mov_b32_e32 v23, v24
	v_mov_b32_e32 v45, v46
	v_pk_fma_f32 v[18:19], v[4:5], v[22:23], v[18:19]
	v_pk_fma_f32 v[40:41], v[4:5], v[44:45], v[40:41]
	v_mov_b32_e32 v24, v21
	v_mov_b32_e32 v46, v43
	v_pk_fma_f32 v[18:19], v[6:7], v[24:25], v[18:19]
	v_pk_fma_f32 v[40:41], v[6:7], v[46:47], v[40:41]
	s_nop 0
	s_add_i32 s19, s19, 4
	v_add_f32_e32 v18, v16, v18
	v_add_f32_e32 v40, v16, v40
	v_add_f32_e32 v22, v18, v19
	v_add_f32_e32 v44, v40, v41
	s_waitcnt lgkmcnt(0)
	s_waitcnt lgkmcnt(0)
	v_mov_b32_e32 v19, v30
	v_mov_b32_e32 v41, v52
	v_mov_b32_e32 v30, v27
	v_mov_b32_e32 v52, v49
	v_mov_b32_e32 v18, v26
	v_mov_b32_e32 v40, v48
	v_pk_mul_f32 v[20:21], v[10:11], v[30:31]
	v_pk_mul_f32 v[42:43], v[10:11], v[52:53]
	s_nop 0
	v_pk_fma_f32 v[40:41], v[8:9], v[40:41], v[42:43]
	v_pk_fma_f32 v[18:19], v[8:9], v[18:19], v[20:21]
	v_mov_b32_e32 v42, v50
	v_mov_b32_e32 v20, v28
	v_mov_b32_e32 v43, v54
	v_mov_b32_e32 v21, v32
	v_pk_fma_f32 v[40:41], v[12:13], v[42:43], v[40:41]
	v_pk_fma_f32 v[18:19], v[12:13], v[20:21], v[18:19]
	v_mov_b32_e32 v54, v51
	v_mov_b32_e32 v32, v29
	v_pk_fma_f32 v[40:41], v[14:15], v[54:55], v[40:41]
	v_pk_fma_f32 v[18:19], v[14:15], v[32:33], v[18:19]
	s_nop 0
	s_nop 0
	v_add_f32_e32 v40, v44, v40
	v_add_f32_e32 v18, v22, v18
	v_add_f32_e32 v40, v40, v41
	v_add_f32_e32 v18, v18, v19
	v_min_f32_e32 v41, 0, v40
	v_min_f32_e32 v19, 0, v18
	v_mul_f32_e64 v40, |v40|, s29
	v_mul_f32_e64 v18, |v18|, s29
	v_exp_f32_e32 v40, v40
	v_exp_f32_e32 v18, v18
	s_nop 0
	s_nop 0
	v_add_f32_e32 v40, 1.0, v40
	v_add_f32_e32 v18, 1.0, v18
	v_cmp_gt_f32_e64 s[98:99], s30, v40
	v_cmp_gt_f32_e32 vcc, s30, v18
	s_nop 1
	s_nop 1
	v_cndmask_b32_e64 v42, 0, 32, s[98:99]
	v_cndmask_b32_e64 v20, 0, 32, vcc
	v_ldexp_f32 v40, v40, v42
	v_ldexp_f32 v18, v18, v20
	v_log_f32_e32 v40, v40
	v_log_f32_e32 v18, v18
	s_nop 0
	s_nop 0
	v_mul_f32_e32 v42, 0x3f317217, v40
	v_mul_f32_e32 v20, 0x3f317217, v18
	v_fma_f32 v42, v40, s31, -v42
	v_fma_f32 v20, v18, s31, -v20
	v_fmac_f32_e32 v42, 0x3377d1cf, v40
	v_fmac_f32_e32 v20, 0x3377d1cf, v18
	v_fmac_f32_e32 v42, 0x3f317217, v40
	v_fmac_f32_e32 v20, 0x3f317217, v18
	v_cmp_lt_f32_e64 s[100:101], |v40|, s34
	v_cmp_lt_f32_e64 s[0:1], |v18|, s34
	s_nop 1
	s_nop 1
	v_cndmask_b32_e64 v40, v40, v42, s[100:101]
	v_cndmask_b32_e64 v18, v18, v20, s[0:1]
	v_cndmask_b32_e64 v42, 0, v239, s[98:99]
	v_cndmask_b32_e32 v20, 0, v239, vcc
	v_sub_f32_e32 v40, v40, v42
	v_sub_f32_e32 v18, v18, v20
	v_sub_f32_e32 v40, v41, v40
	v_sub_f32_e32 v18, v19, v18
	v_fmac_f32_e32 v17, 0x3d800000, v18
	v_lshl_add_u32 v18, v36, 9, v193
	ds_write_b32 v18, v17
	v_lshl_add_u32 v59, v58, 9, v193
	s_nop 1
	v_fmac_f32_e32 v17, 0x3d800000, v40
	ds_write_b32 v59, v17
	s_cmp_lg_u32 s19, 64
	s_cbranch_scc1 .LBB0_495

.LBB0_617:
	s_waitcnt vmcnt(0)
	s_add_i32 s0, s58, 3
	s_add_i32 s100, s58, 2
	v_mov_b32_e32 v18, s0
	s_add_i32 s101, s55, 1
	v_mov_b32_e32 v19, s55
	v_mov_b32_e32 v40, s100
	v_cndmask_b32_e64 v36, v18, v19, s[48:49]
	v_mov_b32_e32 v41, s101
	v_lshl_add_u32 v30, v36, 7, v110
	v_cndmask_b32_e64 v58, v40, v41, s[48:49]
	ds_read_b128 v[18:21], v30
	v_lshl_add_u32 v52, v58, 7, v110
	ds_read_b128 v[22:25], v30 offset:16
	ds_read_b128 v[40:43], v52
	ds_read_b128 v[26:29], v30 offset:32
	ds_read_b128 v[44:47], v52 offset:16
	ds_read_b128 v[30:33], v30 offset:48
	ds_read_b128 v[48:51], v52 offset:32
	s_waitcnt lgkmcnt(0)
	ds_read_b128 v[52:55], v52 offset:48
	v_mov_b32_e32 v34, v18
	s_waitcnt lgkmcnt(0)
	s_waitcnt lgkmcnt(0)
	v_mov_b32_e32 v56, v40
	v_mov_b32_e32 v35, v22
	s_waitcnt lgkmcnt(0)
	v_mov_b32_e32 v22, v19
	v_mov_b32_e32 v57, v44
	v_pk_mul_f32 v[18:19], v[2:3], v[22:23]
	v_mov_b32_e32 v44, v41
	v_mov_b32_e32 v22, v20
	v_pk_mul_f32 v[40:41], v[2:3], v[44:45]
	v_pk_fma_f32 v[18:19], v[0:1], v[34:35], v[18:19]
	v_mov_b32_e32 v44, v42
	v_mov_b32_e32 v23, v24
	v_pk_fma_f32 v[40:41], v[0:1], v[56:57], v[40:41]
	v_pk_fma_f32 v[18:19], v[4:5], v[22:23], v[18:19]
	v_mov_b32_e32 v45, v46
	v_mov_b32_e32 v24, v21
	v_pk_fma_f32 v[40:41], v[4:5], v[44:45], v[40:41]
	v_pk_fma_f32 v[18:19], v[6:7], v[24:25], v[18:19]
	v_mov_b32_e32 v46, v43
	v_add_f32_e32 v18, v16, v18
	v_pk_fma_f32 v[40:41], v[6:7], v[46:47], v[40:41]
	v_add_f32_e32 v22, v18, v19
	s_nop 0
	s_waitcnt lgkmcnt(0)
	v_add_f32_e32 v40, v16, v40
	v_mov_b32_e32 v19, v30
	v_add_f32_e32 v44, v40, v41
	v_mov_b32_e32 v30, v27
	s_waitcnt lgkmcnt(0)
	v_mov_b32_e32 v18, v26
	v_mov_b32_e32 v41, v52
	v_pk_mul_f32 v[20:21], v[10:11], v[30:31]
	v_mov_b32_e32 v52, v49
	s_nop 0
	v_mov_b32_e32 v40, v48
	v_pk_fma_f32 v[18:19], v[8:9], v[18:19], v[20:21]
	v_pk_mul_f32 v[42:43], v[10:11], v[52:53]
	v_mov_b32_e32 v20, v28
	s_nop 0
	v_mov_b32_e32 v21, v32
	v_pk_fma_f32 v[40:41], v[8:9], v[40:41], v[42:43]
	v_pk_fma_f32 v[18:19], v[12:13], v[20:21], v[18:19]
	v_mov_b32_e32 v42, v50
	v_mov_b32_e32 v32, v29
	v_mov_b32_e32 v43, v54
	v_pk_fma_f32 v[18:19], v[14:15], v[32:33], v[18:19]
	v_pk_fma_f32 v[40:41], v[12:13], v[42:43], v[40:41]
	s_nop 0
	v_mov_b32_e32 v54, v51
	v_add_f32_e32 v18, v22, v18
	v_pk_fma_f32 v[40:41], v[14:15], v[54:55], v[40:41]
	v_add_f32_e32 v18, v18, v19
	s_nop 0
	v_min_f32_e32 v19, 0, v18
	v_add_f32_e32 v40, v44, v40
	v_mul_f32_e64 v18, |v18|, s4
	v_add_f32_e32 v40, v40, v41
	v_exp_f32_e32 v18, v18
	v_min_f32_e32 v41, 0, v40
	s_nop 0
	v_mul_f32_e64 v40, |v40|, s4
	v_add_f32_e32 v18, 1.0, v18
	v_exp_f32_e32 v40, v40
	v_cmp_gt_f32_e32 vcc, s5, v18
	s_nop 0
	s_nop 1
	v_add_f32_e32 v40, 1.0, v40
	v_cndmask_b32_e64 v20, 0, 32, vcc
	v_cmp_gt_f32_e64 s[98:99], s5, v40
	v_ldexp_f32 v18, v18, v20
	s_nop 1
	v_log_f32_e32 v18, v18
	v_cndmask_b32_e64 v42, 0, 32, s[98:99]
	s_nop 0
	v_ldexp_f32 v40, v40, v42
	v_mul_f32_e32 v20, 0x3f317217, v18
	v_log_f32_e32 v40, v40
	v_fma_f32 v20, v18, s64, -v20
	s_nop 0
	v_fmac_f32_e32 v20, 0x3377d1cf, v18
	v_mul_f32_e32 v42, 0x3f317217, v40
	v_fmac_f32_e32 v20, 0x3f317217, v18
	v_fma_f32 v42, v40, s64, -v42
	v_cmp_lt_f32_e64 s[0:1], |v18|, s65
	v_fmac_f32_e32 v42, 0x3377d1cf, v40
	s_nop 1
	v_fmac_f32_e32 v42, 0x3f317217, v40
	v_cndmask_b32_e64 v18, v18, v20, s[0:1]
	v_cmp_lt_f32_e64 s[100:101], |v40|, s65
	v_cndmask_b32_e32 v20, 0, v171, vcc
	s_nop 1
	v_sub_f32_e32 v18, v18, v20
	v_cndmask_b32_e64 v40, v40, v42, s[100:101]
	v_sub_f32_e32 v18, v19, v18
	v_cndmask_b32_e64 v42, 0, v171, s[98:99]
	v_sub_f32_e32 v40, v40, v42
	v_sub_f32_e32 v40, v41, v40
	v_fmac_f32_e32 v17, 0x3d800000, v18
	v_lshl_add_u32 v18, v36, 9, v109
	ds_write_b32 v18, v17
	v_lshl_add_u32 v59, v58, 9, v109
	s_nop 1
	v_fmac_f32_e32 v17, 0x3d800000, v40
	ds_write_b32 v59, v17
	s_add_i32 s0, s58, 1
	s_add_i32 s100, s55, 3
	s_add_i32 s1, s55, 2
	v_mov_b32_e32 v40, s58
	v_mov_b32_e32 v18, s0
	v_mov_b32_e32 v41, s100
	v_mov_b32_e32 v19, s1
	v_cndmask_b32_e64 v58, v40, v41, s[48:49]
	v_cndmask_b32_e64 v36, v18, v19, s[48:49]
	v_lshl_add_u32 v52, v58, 7, v110
	v_lshl_add_u32 v30, v36, 7, v110
	ds_read_b128 v[40:43], v52
	ds_read_b128 v[18:21], v30
	ds_read_b128 v[44:47], v52 offset:16
	ds_read_b128 v[22:25], v30 offset:16
	ds_read_b128 v[48:51], v52 offset:32
	ds_read_b128 v[26:29], v30 offset:32
	ds_read_b128 v[52:55], v52 offset:48
	ds_read_b128 v[30:33], v30 offset:48
	s_add_i32 s58, s58, -4
	s_waitcnt lgkmcnt(0)
	s_waitcnt lgkmcnt(0)
	v_mov_b32_e32 v34, v18
	v_mov_b32_e32 v56, v40
	s_waitcnt lgkmcnt(0)
	s_waitcnt lgkmcnt(0)
	v_mov_b32_e32 v35, v22
	v_mov_b32_e32 v57, v44
	v_mov_b32_e32 v22, v19
	v_mov_b32_e32 v44, v41
	v_pk_mul_f32 v[18:19], v[2:3], v[22:23]
	v_pk_mul_f32 v[40:41], v[2:3], v[44:45]
	v_mov_b32_e32 v22, v20
	v_mov_b32_e32 v44, v42
	v_pk_fma_f32 v[18:19], v[0:1], v[34:35], v[18:19]
	v_pk_fma_f32 v[40:41], v[0:1], v[56:57], v[40:41]
	v_mov_b32_e32 v23, v24
	v_mov_b32_e32 v45, v46
	v_pk_fma_f32 v[18:19], v[4:5], v[22:23], v[18:19]
	v_pk_fma_f32 v[40:41], v[4:5], v[44:45], v[40:41]
	v_mov_b32_e32 v24, v21
	v_mov_b32_e32 v46, v43
	v_pk_fma_f32 v[18:19], v[6:7], v[24:25], v[18:19]
	v_pk_fma_f32 v[40:41], v[6:7], v[46:47], v[40:41]
	s_nop 0
	s_add_i32 s55, s55, 4
	v_add_f32_e32 v18, v16, v18
	v_add_f32_e32 v40, v16, v40
	v_add_f32_e32 v22, v18, v19
	v_add_f32_e32 v44, v40, v41
	s_waitcnt lgkmcnt(0)
	s_waitcnt lgkmcnt(0)
	v_mov_b32_e32 v19, v30
	v_mov_b32_e32 v41, v52
	v_mov_b32_e32 v30, v27
	v_mov_b32_e32 v52, v49
	v_mov_b32_e32 v18, v26
	v_mov_b32_e32 v40, v48
	v_pk_mul_f32 v[20:21], v[10:11], v[30:31]
	v_pk_mul_f32 v[42:43], v[10:11], v[52:53]
	s_nop 0
	v_pk_fma_f32 v[40:41], v[8:9], v[40:41], v[42:43]
	v_pk_fma_f32 v[18:19], v[8:9], v[18:19], v[20:21]
	v_mov_b32_e32 v42, v50
	v_mov_b32_e32 v20, v28
	v_mov_b32_e32 v43, v54
	v_mov_b32_e32 v21, v32
	v_pk_fma_f32 v[40:41], v[12:13], v[42:43], v[40:41]
	v_pk_fma_f32 v[18:19], v[12:13], v[20:21], v[18:19]
	v_mov_b32_e32 v54, v51
	v_mov_b32_e32 v32, v29
	v_pk_fma_f32 v[40:41], v[14:15], v[54:55], v[40:41]
	v_pk_fma_f32 v[18:19], v[14:15], v[32:33], v[18:19]
	s_nop 0
	s_nop 0
	v_add_f32_e32 v40, v44, v40
	v_add_f32_e32 v18, v22, v18
	v_add_f32_e32 v40, v40, v41
	v_add_f32_e32 v18, v18, v19
	v_min_f32_e32 v41, 0, v40
	v_min_f32_e32 v19, 0, v18
	v_mul_f32_e64 v40, |v40|, s4
	v_mul_f32_e64 v18, |v18|, s4
	v_exp_f32_e32 v40, v40
	v_exp_f32_e32 v18, v18
	s_nop 0
	s_nop 0
	v_add_f32_e32 v40, 1.0, v40
	v_add_f32_e32 v18, 1.0, v18
	v_cmp_gt_f32_e64 s[98:99], s5, v40
	v_cmp_gt_f32_e32 vcc, s5, v18
	s_nop 1
	s_nop 1
	v_cndmask_b32_e64 v42, 0, 32, s[98:99]
	v_cndmask_b32_e64 v20, 0, 32, vcc
	v_ldexp_f32 v40, v40, v42
	v_ldexp_f32 v18, v18, v20
	v_log_f32_e32 v40, v40
	v_log_f32_e32 v18, v18
	s_nop 0
	s_nop 0
	v_mul_f32_e32 v42, 0x3f317217, v40
	v_mul_f32_e32 v20, 0x3f317217, v18
	v_fma_f32 v42, v40, s64, -v42
	v_fma_f32 v20, v18, s64, -v20
	v_fmac_f32_e32 v42, 0x3377d1cf, v40
	v_fmac_f32_e32 v20, 0x3377d1cf, v18
	v_fmac_f32_e32 v42, 0x3f317217, v40
	v_fmac_f32_e32 v20, 0x3f317217, v18
	v_cmp_lt_f32_e64 s[100:101], |v40|, s65
	v_cmp_lt_f32_e64 s[0:1], |v18|, s65
	s_nop 1
	s_nop 1
	v_cndmask_b32_e64 v40, v40, v42, s[100:101]
	v_cndmask_b32_e64 v18, v18, v20, s[0:1]
	v_cndmask_b32_e64 v42, 0, v171, s[98:99]
	v_cndmask_b32_e32 v20, 0, v171, vcc
	v_sub_f32_e32 v40, v40, v42
	v_sub_f32_e32 v18, v18, v20
	v_sub_f32_e32 v40, v41, v40
	v_sub_f32_e32 v18, v19, v18
	v_fmac_f32_e32 v17, 0x3d800000, v18
	v_lshl_add_u32 v18, v36, 9, v109
	ds_write_b32 v18, v17
	v_lshl_add_u32 v59, v58, 9, v109
	s_nop 1
	v_fmac_f32_e32 v17, 0x3d800000, v40
	ds_write_b32 v59, v17
	s_cmp_lg_u32 s55, 64
	s_cbranch_scc1 .LBB0_617

	.amdhsa_kernel _Z8mega_fwd6Params
		.amdhsa_group_segment_fixed_size 0
		.amdhsa_private_segment_fixed_size 0
		.amdhsa_kernarg_size 568
		.amdhsa_user_sgpr_count 2
		.amdhsa_user_sgpr_dispatch_ptr 0
		.amdhsa_user_sgpr_queue_ptr 0
		.amdhsa_user_sgpr_kernarg_segment_ptr 1
		.amdhsa_user_sgpr_dispatch_id 0
		.amdhsa_user_sgpr_kernarg_preload_length 0
		.amdhsa_user_sgpr_kernarg_preload_offset 0
		.amdhsa_user_sgpr_private_segment_size 0
		.amdhsa_uses_dynamic_stack 0
		.amdhsa_enable_private_segment 0
		.amdhsa_system_sgpr_workgroup_id_x 1
		.amdhsa_system_sgpr_workgroup_id_y 0
		.amdhsa_system_sgpr_workgroup_id_z 0
		.amdhsa_system_sgpr_workgroup_info 0
		.amdhsa_system_vgpr_workitem_id 2
		.amdhsa_next_free_vgpr 245
		.amdhsa_next_free_sgpr 102
		.amdhsa_accum_offset 248
		.amdhsa_reserve_vcc 1
		.amdhsa_float_round_mode_32 0
		.amdhsa_float_round_mode_16_64 0
		.amdhsa_float_denorm_mode_32 3
		.amdhsa_float_denorm_mode_16_64 3
		.amdhsa_dx10_clamp 1
		.amdhsa_ieee_mode 1
		.amdhsa_fp16_overflow 0
		.amdhsa_tg_split 0
		.amdhsa_exception_fp_ieee_invalid_op 0
		.amdhsa_exception_fp_denorm_src 0
		.amdhsa_exception_fp_ieee_div_zero 0
		.amdhsa_exception_fp_ieee_overflow 0
		.amdhsa_exception_fp_ieee_underflow 0
		.amdhsa_exception_fp_ieee_inexact 0
		.amdhsa_exception_int_div_zero 0
	.end_amdhsa_kernel

amdhsa.kernels:
  - .agpr_count:     0
    .args:
      - .offset:         0
        .size:           312
        .value_kind:     by_value
      - .offset:         312
        .size:           4
        .value_kind:     hidden_block_count_x
      - .offset:         316
        .size:           4
        .value_kind:     hidden_block_count_y
      - .offset:         320
        .size:           4
        .value_kind:     hidden_block_count_z
      - .offset:         324
        .size:           2
        .value_kind:     hidden_group_size_x
      - .offset:         326
        .size:           2
        .value_kind:     hidden_group_size_y
      - .offset:         328
        .size:           2
        .value_kind:     hidden_group_size_z
      - .offset:         330
        .size:           2
        .value_kind:     hidden_remainder_x
      - .offset:         332
        .size:           2
        .value_kind:     hidden_remainder_y
      - .offset:         334
        .size:           2
        .value_kind:     hidden_remainder_z
      - .offset:         352
        .size:           8
        .value_kind:     hidden_global_offset_x
      - .offset:         360
        .size:           8
        .value_kind:     hidden_global_offset_y
      - .offset:         368
        .size:           8
        .value_kind:     hidden_global_offset_z
      - .offset:         376
        .size:           2
        .value_kind:     hidden_grid_dims
      - .offset:         400
        .size:           8
        .value_kind:     hidden_multigrid_sync_arg
      - .offset:         432
        .size:           4
        .value_kind:     hidden_dynamic_lds_size
    .group_segment_fixed_size: 0
    .kernarg_segment_align: 8
    .kernarg_segment_size: 568
    .language:       OpenCL C
    .language_version:
      - 2
      - 0
    .max_flat_workgroup_size: 512
    .name:           _Z8mega_fwd6Params
    .private_segment_fixed_size: 0
    .sgpr_count:     108
    .sgpr_spill_count: 63
    .symbol:         _Z8mega_fwd6Params.kd
    .uniform_work_group_size: 1
    .uses_dynamic_stack: false
    .vgpr_count:     245
    .vgpr_spill_count: 0
    .wavefront_size: 64
